# MERGE1 epilogue: gate/MRG loads hoisted ahead of the epilogue into free fragment registers, counted vmcnt waits
# speedup vs baseline: 1.0009x; 1.0009x over previous
; #define PG8_STAGE(bufoff, gbase, voff) do { _Pragma("unroll") for (int _i = 0; _i < 2; ++_i) \
;         __builtin_amdgcn_global_load_lds((const unsigned*)((const char*)(gbase) + (voff)[_i]), (PG8_LAS unsigned*)(lds + (bufoff) + ldsw + _i * 8192), 16, 0, 0); } while (0)
; #define PG8_LDA(dst, b, h) do { _Pragma("unroll") for (int m = 0; m < 4; ++m) _Pragma("unroll") for (int k = 0; k < 2; ++k) dst[m][k] = *(const PG8_LAS bf16x8*)(lds + PG8_SA(b, h) + aoff + m * 2048 + k * 1024); } while (0)
; #define PG8_LDB(dst, b, h) do { _Pragma("unroll") for (int n = 0; n < 2; ++n) _Pragma("unroll") for (int k = 0; k < 2; ++k) dst[n][k] = *(const PG8_LAS bf16x8*)(lds + PG8_SB(b, h) + boff + n * 2048 + k * 1024); } while (0)
; #define PG8_MMA(ai, bj, At, Bt) do { __builtin_amdgcn_s_setprio(1); _Pragma("unroll") for (int m = 0; m < 4; ++m) _Pragma("unroll") for (int n = 0; n < 2; ++n) _Pragma("unroll") for (int k = 0; k < 2; ++k) \
;         acc[ai][bj][m][n] = __builtin_amdgcn_mfma_f32_16x16x32_bf16(Bt[n][k], At[m][k], acc[ai][bj][m][n], 0, 0, 0); __builtin_amdgcn_s_setprio(0); } while (0)
; #define PG8_WAIT_V(n) asm volatile("s_waitcnt vmcnt(" #n ")" ::: "memory")
; #define PG8_BAR __builtin_amdgcn_s_barrier()
; template <class Epi, class Sched, bool ALIGN_EPI = false, bool SP2 = false>
; __device__ __forceinline__ void gemm_phase(PG8_LAS unsigned char* lds, const Gemm g, const Sched& S, const Epi& E, int wave_in) {
;     ...
;         for (int t = 0; t < nt; t += 2) {
;             const bool last = (t == nt - 2);
;             const char* a1 = cA + (size_t)(t + 1) * kstep;
;             const char* a2 = last ? nA : cA + (size_t)(t + 2) * kstep; const char* b2 = last ? nB : cB + (size_t)(t + 2) * kstep;
;             const char* a3 = a2 + kstep; const char* b3 = b2 + kstep;
;             if (last && has_next) S.a_ready(nxt);
;             if constexpr (SP2) {
;             PG8_LDB(B0, 0, 0); PG8_LDB(B1, 0, 1); PG8_SCHED; PG8_LDA(At, 0, 0); PG8_STAGE(PG8_SA(1, 1), a1 + hstepA, voffA);
;             PG8_WAIT_V(8); PG8_WAIT_L(0); PG8_BAR; PG8_MMA(0, 0, At, B0); PG8_MMA(0, 1, At, B1); PG8_BAR; PG8_SCHED;
;             PG8_LDA(At, 0, 1); PG8_STAGE(PG8_SB(0, 0), b2, voffB); PG8_STAGE(PG8_SB(0, 1), b2 + hstep, voffB); PG8_STAGE(PG8_SA(0, 0), a2, voffA);
;             PG8_WAIT_V(8); PG8_WAIT_L(0); PG8_BAR; PG8_MMA(1, 0, At, B0); PG8_MMA(1, 1, At, B1); PG8_BAR; PG8_SCHED;
.LBB0_107:
	s_add_u32 s28, s26, 0xfff80080
	s_addc_u32 s29, s27, -1
	s_add_i32 s55, 0, 0x10000
	s_cmp_eq_u32 s54, 4
	s_cselect_b32 s31, s21, s29
	s_cselect_b32 s30, s50, s28
	v_add_u32_e32 v144, s55, v147
	s_cselect_b32 s29, s19, s53
	s_cselect_b32 s28, s51, s52
	s_add_i32 s58, 0, 0x14000
	ds_read_b128 v[140:143], v144
	ds_read_b128 v[150:153], v144 offset:1024
	ds_read_b128 v[154:157], v144 offset:2048
	ds_read_b128 v[168:171], v144 offset:3072
	v_add_u32_e32 v144, s58, v147
	ds_read_b128 v[172:175], v144
	ds_read_b128 v[176:179], v144 offset:1024
	ds_read_b128 v[180:183], v144 offset:2048
	ds_read_b128 v[184:187], v144 offset:3072
	v_lshl_add_u64 v[144:145], s[26:27], 0, v[136:137]
	s_add_i32 m0, s41, 0xc000
	ds_read_b128 v[188:191], v149
	ds_read_b128 v[212:215], v149 offset:1024
	ds_read_b128 v[216:219], v149 offset:2048
	ds_read_b128 v[220:223], v149 offset:3072
	ds_read_b128 v[224:227], v149 offset:4096
	ds_read_b128 v[228:231], v149 offset:5120
	ds_read_b128 v[232:235], v149 offset:6144
	ds_read_b128 v[236:239], v149 offset:7168
	global_load_lds_dwordx4 v[144:145], off
	v_lshl_add_u64 v[144:145], s[26:27], 0, v[138:139]
	s_add_i32 m0, s41, 0xe000
	s_nop 0
	global_load_lds_dwordx4 v[144:145], off
	s_waitcnt vmcnt(8)
	s_waitcnt lgkmcnt(0)
	s_barrier
	s_setprio 1
	s_waitcnt lgkmcnt(0)
	v_mfma_f32_16x16x32_bf16 v[126:129], v[140:143], v[188:191], v[126:129]
	v_mfma_f32_16x16x32_bf16 v[122:125], v[154:157], v[188:191], v[122:125]
	v_mfma_f32_16x16x32_bf16 v[110:113], v[140:143], v[216:219], v[110:113]
	v_mfma_f32_16x16x32_bf16 v[106:109], v[154:157], v[216:219], v[106:109]
	v_mfma_f32_16x16x32_bf16 v[94:97], v[140:143], v[224:227], v[94:97]
	v_mfma_f32_16x16x32_bf16 v[90:93], v[154:157], v[224:227], v[90:93]
	v_mfma_f32_16x16x32_bf16 v[78:81], v[140:143], v[232:235], v[78:81]
	v_mfma_f32_16x16x32_bf16 v[74:77], v[154:157], v[232:235], v[74:77]
	v_mfma_f32_16x16x32_bf16 v[126:129], v[150:153], v[212:215], v[126:129]
	v_mfma_f32_16x16x32_bf16 v[122:125], v[168:171], v[212:215], v[122:125]
	v_mfma_f32_16x16x32_bf16 v[110:113], v[150:153], v[220:223], v[110:113]
	v_mfma_f32_16x16x32_bf16 v[106:109], v[168:171], v[220:223], v[106:109]
	v_mfma_f32_16x16x32_bf16 v[94:97], v[150:153], v[228:231], v[94:97]
	v_mfma_f32_16x16x32_bf16 v[90:93], v[168:171], v[228:231], v[90:93]
	v_mfma_f32_16x16x32_bf16 v[78:81], v[150:153], v[236:239], v[78:81]
	v_mfma_f32_16x16x32_bf16 v[74:77], v[168:171], v[236:239], v[74:77]
	s_setprio 0
	s_setprio 1
	v_mfma_f32_16x16x32_bf16 v[118:121], v[172:175], v[188:191], v[118:121]
	v_mfma_f32_16x16x32_bf16 v[114:117], v[180:183], v[188:191], v[114:117]
	v_mfma_f32_16x16x32_bf16 v[102:105], v[172:175], v[216:219], v[102:105]
	v_mfma_f32_16x16x32_bf16 v[98:101], v[180:183], v[216:219], v[98:101]
	v_mfma_f32_16x16x32_bf16 v[86:89], v[172:175], v[224:227], v[86:89]
	v_mfma_f32_16x16x32_bf16 v[82:85], v[180:183], v[224:227], v[82:85]
	v_mfma_f32_16x16x32_bf16 v[70:73], v[172:175], v[232:235], v[70:73]
	v_mfma_f32_16x16x32_bf16 v[66:69], v[180:183], v[232:235], v[66:69]
	v_mfma_f32_16x16x32_bf16 v[118:121], v[176:179], v[212:215], v[118:121]
	v_mfma_f32_16x16x32_bf16 v[114:117], v[184:187], v[212:215], v[114:117]
	v_mfma_f32_16x16x32_bf16 v[102:105], v[176:179], v[220:223], v[102:105]
	v_mfma_f32_16x16x32_bf16 v[98:101], v[184:187], v[220:223], v[98:101]
	v_mfma_f32_16x16x32_bf16 v[86:89], v[176:179], v[228:231], v[86:89]
	v_mfma_f32_16x16x32_bf16 v[82:85], v[184:187], v[228:231], v[82:85]
	v_mfma_f32_16x16x32_bf16 v[70:73], v[176:179], v[236:239], v[70:73]
	v_mfma_f32_16x16x32_bf16 v[66:69], v[184:187], v[236:239], v[66:69]
	s_setprio 0
	s_barrier
	s_add_i32 s55, s55, s40
	v_lshl_add_u64 v[144:145], s[28:29], 0, v[0:1]
	s_mov_b32 m0, s55
	ds_read_b128 v[188:191], v149 offset:16384
	ds_read_b128 v[212:215], v149 offset:17408
	ds_read_b128 v[216:219], v149 offset:18432
	ds_read_b128 v[220:223], v149 offset:19456
	ds_read_b128 v[224:227], v149 offset:20480
	ds_read_b128 v[228:231], v149 offset:21504
	ds_read_b128 v[232:235], v149 offset:22528
	ds_read_b128 v[236:239], v149 offset:23552
	global_load_lds_dwordx4 v[144:145], off
	s_add_i32 m0, s55, 0x2000
	s_add_u32 s56, s28, 0x20000
	v_lshl_add_u64 v[192:193], s[28:29], 0, v[130:131]
	s_addc_u32 s57, s29, 0
	s_add_i32 s55, s58, s40
	global_load_lds_dwordx4 v[192:193], off
	v_lshl_add_u64 v[240:241], s[56:57], 0, v[0:1]
	s_mov_b32 m0, s55
	v_lshl_add_u64 v[242:243], s[30:31], 0, v[132:133]
	global_load_lds_dwordx4 v[240:241], off
	v_lshl_add_u64 v[240:241], s[56:57], 0, v[130:131]
	s_add_i32 m0, s55, 0x2000
	s_nop 0
	global_load_lds_dwordx4 v[240:241], off
	v_lshl_add_u64 v[240:241], s[30:31], 0, v[134:135]
	s_mov_b32 m0, s41
	s_nop 0
	global_load_lds_dwordx4 v[240:241], off
	s_mov_b32 m0, s42
	s_nop 0
	global_load_lds_dwordx4 v[242:243], off
	s_waitcnt vmcnt(8)
	s_waitcnt lgkmcnt(0)
	s_barrier
; #define PG8_STAGE(bufoff, gbase, voff) do { _Pragma("unroll") for (int _i = 0; _i < 2; ++_i) \
;         __builtin_amdgcn_global_load_lds((const unsigned*)((const char*)(gbase) + (voff)[_i]), (PG8_LAS unsigned*)(lds + (bufoff) + ldsw + _i * 8192), 16, 0, 0); } while (0)
; #define PG8_LDA(dst, b, h) do { _Pragma("unroll") for (int m = 0; m < 4; ++m) _Pragma("unroll") for (int k = 0; k < 2; ++k) dst[m][k] = *(const PG8_LAS bf16x8*)(lds + PG8_SA(b, h) + aoff + m * 2048 + k * 1024); } while (0)
; #define PG8_LDB(dst, b, h) do { _Pragma("unroll") for (int n = 0; n < 2; ++n) _Pragma("unroll") for (int k = 0; k < 2; ++k) dst[n][k] = *(const PG8_LAS bf16x8*)(lds + PG8_SB(b, h) + boff + n * 2048 + k * 1024); } while (0)
; #define PG8_MMA(ai, bj, At, Bt) do { __builtin_amdgcn_s_setprio(1); _Pragma("unroll") for (int m = 0; m < 4; ++m) _Pragma("unroll") for (int n = 0; n < 2; ++n) _Pragma("unroll") for (int k = 0; k < 2; ++k) \
;         acc[ai][bj][m][n] = __builtin_amdgcn_mfma_f32_16x16x32_bf16(Bt[n][k], At[m][k], acc[ai][bj][m][n], 0, 0, 0); __builtin_amdgcn_s_setprio(0); } while (0)
; #define PG8_WAIT_V(n) asm volatile("s_waitcnt vmcnt(" #n ")" ::: "memory")
; #define PG8_WAIT_L(n) asm volatile("s_waitcnt lgkmcnt(" #n ")" ::: "memory")
; #define PG8_BAR __builtin_amdgcn_s_barrier()
; #define PG8_SCHED __builtin_amdgcn_sched_barrier(0)
; template <class Epi, class Sched, bool ALIGN_EPI = false, bool SP2 = false>
; __device__ __forceinline__ void gemm_phase(PG8_LAS unsigned char* lds, const Gemm g, const Sched& S, const Epi& E, int wave_in) {
;     ...
;             PG8_WAIT_V(8); PG8_WAIT_L(0); PG8_BAR; PG8_MMA(1, 0, At, B0); PG8_MMA(1, 1, At, B1); PG8_BAR; PG8_SCHED;
;             PG8_LDB(B0, 1, 0); PG8_LDB(B1, 1, 1); PG8_SCHED; PG8_LDA(At, 1, 0); PG8_STAGE(PG8_SA(0, 1), a2 + hstepA, voffA);
;             PG8_WAIT_V(8); PG8_WAIT_L(0); PG8_BAR; PG8_MMA(0, 0, At, B0); PG8_MMA(0, 1, At, B1); PG8_BAR; PG8_SCHED;
	s_setprio 1
	s_waitcnt lgkmcnt(0)
	v_mfma_f32_16x16x32_bf16 v[62:65], v[140:143], v[188:191], v[62:65]
	v_mfma_f32_16x16x32_bf16 v[58:61], v[154:157], v[188:191], v[58:61]
	v_mfma_f32_16x16x32_bf16 v[46:49], v[140:143], v[216:219], v[46:49]
	v_mfma_f32_16x16x32_bf16 v[42:45], v[154:157], v[216:219], v[42:45]
	v_mfma_f32_16x16x32_bf16 v[30:33], v[140:143], v[224:227], v[30:33]
	v_mfma_f32_16x16x32_bf16 v[26:29], v[154:157], v[224:227], v[26:29]
	v_mfma_f32_16x16x32_bf16 v[14:17], v[140:143], v[232:235], v[14:17]
	v_mfma_f32_16x16x32_bf16 v[10:13], v[154:157], v[232:235], v[10:13]
	v_mfma_f32_16x16x32_bf16 v[62:65], v[150:153], v[212:215], v[62:65]
	v_mfma_f32_16x16x32_bf16 v[58:61], v[168:171], v[212:215], v[58:61]
	v_mfma_f32_16x16x32_bf16 v[46:49], v[150:153], v[220:223], v[46:49]
	v_mfma_f32_16x16x32_bf16 v[42:45], v[168:171], v[220:223], v[42:45]
	v_mfma_f32_16x16x32_bf16 v[30:33], v[150:153], v[228:231], v[30:33]
	v_mfma_f32_16x16x32_bf16 v[26:29], v[168:171], v[228:231], v[26:29]
	v_mfma_f32_16x16x32_bf16 v[14:17], v[150:153], v[236:239], v[14:17]
	v_mfma_f32_16x16x32_bf16 v[10:13], v[168:171], v[236:239], v[10:13]
	s_setprio 0
	s_setprio 1
	v_mfma_f32_16x16x32_bf16 v[54:57], v[172:175], v[188:191], v[54:57]
	v_mfma_f32_16x16x32_bf16 v[50:53], v[180:183], v[188:191], v[50:53]
	v_mfma_f32_16x16x32_bf16 v[38:41], v[172:175], v[216:219], v[38:41]
	v_mfma_f32_16x16x32_bf16 v[34:37], v[180:183], v[216:219], v[34:37]
	v_mfma_f32_16x16x32_bf16 v[22:25], v[172:175], v[224:227], v[22:25]
	v_mfma_f32_16x16x32_bf16 v[18:21], v[180:183], v[224:227], v[18:21]
	v_mfma_f32_16x16x32_bf16 v[6:9], v[172:175], v[232:235], v[6:9]
	v_mfma_f32_16x16x32_bf16 v[2:5], v[180:183], v[232:235], v[2:5]
	v_mfma_f32_16x16x32_bf16 v[54:57], v[176:179], v[212:215], v[54:57]
	v_mfma_f32_16x16x32_bf16 v[50:53], v[184:187], v[212:215], v[50:53]
	v_mfma_f32_16x16x32_bf16 v[38:41], v[176:179], v[220:223], v[38:41]
	v_mfma_f32_16x16x32_bf16 v[34:37], v[184:187], v[220:223], v[34:37]
	v_mfma_f32_16x16x32_bf16 v[22:25], v[176:179], v[228:231], v[22:25]
	v_mfma_f32_16x16x32_bf16 v[18:21], v[184:187], v[228:231], v[18:21]
	v_mfma_f32_16x16x32_bf16 v[6:9], v[176:179], v[236:239], v[6:9]
	v_mfma_f32_16x16x32_bf16 v[2:5], v[184:187], v[236:239], v[2:5]
	s_setprio 0
	s_barrier
	s_add_i32 s55, 0, 0x18000
	s_add_i32 s56, 0, 0x1c000
	v_add_u32_e32 v168, s55, v147
	v_add_u32_e32 v184, s56, v147
	ds_read_b128 v[140:143], v168
	ds_read_b128 v[150:153], v168 offset:1024
	ds_read_b128 v[154:157], v168 offset:2048
	ds_read_b128 v[168:171], v168 offset:3072
	ds_read_b128 v[172:175], v184
	ds_read_b128 v[176:179], v184 offset:1024
	ds_read_b128 v[180:183], v184 offset:2048
	ds_read_b128 v[184:187], v184 offset:3072
	s_add_u32 s30, s30, 0x80000
	s_addc_u32 s31, s31, 0
	s_mov_b32 m0, s43
	v_lshl_add_u64 v[244:245], s[30:31], 0, v[134:135]
	ds_read_b128 v[188:191], v149 offset:32768
	ds_read_b128 v[212:215], v149 offset:33792
	ds_read_b128 v[216:219], v149 offset:34816
	ds_read_b128 v[220:223], v149 offset:35840
	ds_read_b128 v[224:227], v149 offset:36864
	ds_read_b128 v[228:231], v149 offset:37888
	ds_read_b128 v[232:235], v149 offset:38912
	ds_read_b128 v[236:239], v149 offset:39936
	global_load_lds_dwordx4 v[244:245], off
	v_lshl_add_u64 v[244:245], s[30:31], 0, v[132:133]
	s_mov_b32 m0, s44
	s_nop 0
	global_load_lds_dwordx4 v[244:245], off
	s_waitcnt vmcnt(8)
	s_waitcnt lgkmcnt(0)
	s_barrier
	s_setprio 1
	s_waitcnt lgkmcnt(0)
	v_mfma_f32_16x16x32_bf16 v[126:129], v[140:143], v[188:191], v[126:129]
	v_mfma_f32_16x16x32_bf16 v[122:125], v[154:157], v[188:191], v[122:125]
	v_mfma_f32_16x16x32_bf16 v[110:113], v[140:143], v[216:219], v[110:113]
	v_mfma_f32_16x16x32_bf16 v[106:109], v[154:157], v[216:219], v[106:109]
	v_mfma_f32_16x16x32_bf16 v[94:97], v[140:143], v[224:227], v[94:97]
	v_mfma_f32_16x16x32_bf16 v[90:93], v[154:157], v[224:227], v[90:93]
	v_mfma_f32_16x16x32_bf16 v[78:81], v[140:143], v[232:235], v[78:81]
	v_mfma_f32_16x16x32_bf16 v[74:77], v[154:157], v[232:235], v[74:77]
	v_mfma_f32_16x16x32_bf16 v[126:129], v[150:153], v[212:215], v[126:129]
	v_mfma_f32_16x16x32_bf16 v[122:125], v[168:171], v[212:215], v[122:125]
	v_mfma_f32_16x16x32_bf16 v[110:113], v[150:153], v[220:223], v[110:113]
	v_mfma_f32_16x16x32_bf16 v[106:109], v[168:171], v[220:223], v[106:109]
	v_mfma_f32_16x16x32_bf16 v[94:97], v[150:153], v[228:231], v[94:97]
	v_mfma_f32_16x16x32_bf16 v[90:93], v[168:171], v[228:231], v[90:93]
	v_mfma_f32_16x16x32_bf16 v[78:81], v[150:153], v[236:239], v[78:81]
	v_mfma_f32_16x16x32_bf16 v[74:77], v[168:171], v[236:239], v[74:77]
	s_setprio 0
	s_setprio 1
	v_mfma_f32_16x16x32_bf16 v[118:121], v[172:175], v[188:191], v[118:121]
	v_mfma_f32_16x16x32_bf16 v[114:117], v[180:183], v[188:191], v[114:117]
	v_mfma_f32_16x16x32_bf16 v[102:105], v[172:175], v[216:219], v[102:105]
	v_mfma_f32_16x16x32_bf16 v[98:101], v[180:183], v[216:219], v[98:101]
	v_mfma_f32_16x16x32_bf16 v[86:89], v[172:175], v[224:227], v[86:89]
	v_mfma_f32_16x16x32_bf16 v[82:85], v[180:183], v[224:227], v[82:85]
	v_mfma_f32_16x16x32_bf16 v[70:73], v[172:175], v[232:235], v[70:73]
	v_mfma_f32_16x16x32_bf16 v[66:69], v[180:183], v[232:235], v[66:69]
	v_mfma_f32_16x16x32_bf16 v[118:121], v[176:179], v[212:215], v[118:121]
	v_mfma_f32_16x16x32_bf16 v[114:117], v[184:187], v[212:215], v[114:117]
	v_mfma_f32_16x16x32_bf16 v[102:105], v[176:179], v[220:223], v[102:105]
	v_mfma_f32_16x16x32_bf16 v[98:101], v[184:187], v[220:223], v[98:101]
	v_mfma_f32_16x16x32_bf16 v[86:89], v[176:179], v[228:231], v[86:89]
	v_mfma_f32_16x16x32_bf16 v[82:85], v[184:187], v[228:231], v[82:85]
	v_mfma_f32_16x16x32_bf16 v[70:73], v[176:179], v[236:239], v[70:73]
	v_mfma_f32_16x16x32_bf16 v[66:69], v[184:187], v[236:239], v[66:69]
	s_setprio 0
	s_barrier
; __device__ __forceinline__ u32x4 pack8(f32x4 a, f32x4 b) { u32x4 w; w.x = cvt_pk_bf16(a[0], a[1]); w.y = cvt_pk_bf16(a[2], a[3]); w.z = cvt_pk_bf16(b[0], b[1]); w.w = cvt_pk_bf16(b[2], b[3]); return w; }
; __device__ __forceinline__ void unpack8(u32x4 w, f32x4& a, f32x4& b) { a = (f32x4){bf_lo(w.x), bf_hi(w.x), bf_lo(w.y), bf_hi(w.y)}; b = (f32x4){bf_lo(w.z), bf_hi(w.z), bf_lo(w.w), bf_hi(w.w)}; }
; #define PG8_STAGE(bufoff, gbase, voff) do { _Pragma("unroll") for (int _i = 0; _i < 2; ++_i) \
;         __builtin_amdgcn_global_load_lds((const unsigned*)((const char*)(gbase) + (voff)[_i]), (PG8_LAS unsigned*)(lds + (bufoff) + ldsw + _i * 8192), 16, 0, 0); } while (0)
; #define PG8_LDA(dst, b, h) do { _Pragma("unroll") for (int m = 0; m < 4; ++m) _Pragma("unroll") for (int k = 0; k < 2; ++k) dst[m][k] = *(const PG8_LAS bf16x8*)(lds + PG8_SA(b, h) + aoff + m * 2048 + k * 1024); } while (0)
; #define PG8_MMA(ai, bj, At, Bt) do { __builtin_amdgcn_s_setprio(1); _Pragma("unroll") for (int m = 0; m < 4; ++m) _Pragma("unroll") for (int n = 0; n < 2; ++n) _Pragma("unroll") for (int k = 0; k < 2; ++k) \
;         acc[ai][bj][m][n] = __builtin_amdgcn_mfma_f32_16x16x32_bf16(Bt[n][k], At[m][k], acc[ai][bj][m][n], 0, 0, 0); __builtin_amdgcn_s_setprio(0); } while (0)
;     __device__ __forceinline__ void operator()(const f32x4 (&acc)[2][2][4][2], const Unit& u, int wr, int wc, int fr, int fq) const {
;     ...
;                     } else if (MODE == EP_MERGE0 || MODE == EP_MERGE1) {
;                         f32x4 g0, g1; unpack8(*(const u32x4*)(aux + row * ldaux + col), g0, g1);
;                         v0 = g0 * v0; v1 = g1 * v1;
;                         if (MODE == EP_MERGE1) { f32x4 o0, o1; unpack8(*(const u32x4*)((const bf16_t*)O + row * ldc + col), o0, o1); v0 = v0 + o0; v1 = v1 + o1; }
;                         *(u32x4*)((bf16_t*)O + row * ldc + col) = pack8(v0, v1);
; template <class Epi, class Sched, bool ALIGN_EPI = false, bool SP2 = false>
; __device__ __forceinline__ void gemm_phase(PG8_LAS unsigned char* lds, const Gemm g, const Sched& S, const Epi& E, int wave_in) {
;     ...
;             PG8_LDA(At, 1, 1); PG8_STAGE(PG8_SB(1, 0), b3, voffB); PG8_STAGE(PG8_SB(1, 1), b3 + hstep, voffB); PG8_STAGE(PG8_SA(1, 0), a3, voffA);
;             PG8_WAIT_V(8); PG8_WAIT_L(0); PG8_BAR; PG8_MMA(1, 0, At, B0); PG8_MMA(1, 1, At, B1); PG8_BAR; PG8_SCHED;
	s_add_i32 s30, s55, s40
	v_lshl_add_u64 v[144:145], v[144:145], 0, s[84:85]
	s_mov_b32 m0, s30
	ds_read_b128 v[188:191], v149 offset:49152
	ds_read_b128 v[212:215], v149 offset:50176
	ds_read_b128 v[216:219], v149 offset:51200
	ds_read_b128 v[220:223], v149 offset:52224
	ds_read_b128 v[224:227], v149 offset:53248
	ds_read_b128 v[228:231], v149 offset:54272
	ds_read_b128 v[232:235], v149 offset:55296
	ds_read_b128 v[236:239], v149 offset:56320
	global_load_lds_dwordx4 v[144:145], off
	s_add_i32 m0, s30, 0x2000
	s_add_u32 s28, s28, 0x20080
	v_lshl_add_u64 v[144:145], v[192:193], 0, s[84:85]
	s_addc_u32 s29, s29, 0
	s_add_i32 s30, s56, s40
	global_load_lds_dwordx4 v[144:145], off
	v_lshl_add_u64 v[144:145], s[28:29], 0, v[0:1]
	s_mov_b32 m0, s30
	s_nop 0
	global_load_lds_dwordx4 v[144:145], off
	v_lshl_add_u64 v[144:145], s[28:29], 0, v[130:131]
	s_add_i32 m0, s30, 0x2000
	s_nop 0
	global_load_lds_dwordx4 v[144:145], off
	v_lshl_add_u64 v[144:145], v[240:241], 0, s[84:85]
	s_mov_b32 m0, s45
	s_nop 0
	global_load_lds_dwordx4 v[144:145], off
	v_lshl_add_u64 v[144:145], v[242:243], 0, s[84:85]
	s_mov_b32 m0, s46
	s_nop 0
	global_load_lds_dwordx4 v[144:145], off
	s_waitcnt vmcnt(8)
	s_waitcnt lgkmcnt(0)
	s_barrier
	s_setprio 1
	s_waitcnt lgkmcnt(0)
	v_mfma_f32_16x16x32_bf16 v[62:65], v[140:143], v[188:191], v[62:65]
	v_mfma_f32_16x16x32_bf16 v[58:61], v[154:157], v[188:191], v[58:61]
	v_mfma_f32_16x16x32_bf16 v[46:49], v[140:143], v[216:219], v[46:49]
	v_mfma_f32_16x16x32_bf16 v[42:45], v[154:157], v[216:219], v[42:45]
	v_mfma_f32_16x16x32_bf16 v[30:33], v[140:143], v[224:227], v[30:33]
	v_mfma_f32_16x16x32_bf16 v[26:29], v[154:157], v[224:227], v[26:29]
	v_mfma_f32_16x16x32_bf16 v[14:17], v[140:143], v[232:235], v[14:17]
	v_mfma_f32_16x16x32_bf16 v[10:13], v[154:157], v[232:235], v[10:13]
	v_mfma_f32_16x16x32_bf16 v[62:65], v[150:153], v[212:215], v[62:65]
	v_mfma_f32_16x16x32_bf16 v[58:61], v[168:171], v[212:215], v[58:61]
	v_mfma_f32_16x16x32_bf16 v[46:49], v[150:153], v[220:223], v[46:49]
	v_mfma_f32_16x16x32_bf16 v[42:45], v[168:171], v[220:223], v[42:45]
	v_mfma_f32_16x16x32_bf16 v[30:33], v[150:153], v[228:231], v[30:33]
	v_mfma_f32_16x16x32_bf16 v[26:29], v[168:171], v[228:231], v[26:29]
	v_mfma_f32_16x16x32_bf16 v[14:17], v[150:153], v[236:239], v[14:17]
	v_mfma_f32_16x16x32_bf16 v[10:13], v[168:171], v[236:239], v[10:13]
	s_setprio 0
	s_setprio 1
	v_mfma_f32_16x16x32_bf16 v[54:57], v[172:175], v[188:191], v[54:57]
	v_mfma_f32_16x16x32_bf16 v[50:53], v[180:183], v[188:191], v[50:53]
	v_mfma_f32_16x16x32_bf16 v[38:41], v[172:175], v[216:219], v[38:41]
	v_mfma_f32_16x16x32_bf16 v[34:37], v[180:183], v[216:219], v[34:37]
	v_mfma_f32_16x16x32_bf16 v[22:25], v[172:175], v[224:227], v[22:25]
	v_mfma_f32_16x16x32_bf16 v[18:21], v[180:183], v[224:227], v[18:21]
	v_mfma_f32_16x16x32_bf16 v[6:9], v[172:175], v[232:235], v[6:9]
	v_mfma_f32_16x16x32_bf16 v[2:5], v[180:183], v[232:235], v[2:5]
	v_mfma_f32_16x16x32_bf16 v[54:57], v[176:179], v[212:215], v[54:57]
	v_mfma_f32_16x16x32_bf16 v[50:53], v[184:187], v[212:215], v[50:53]
	v_mfma_f32_16x16x32_bf16 v[38:41], v[176:179], v[220:223], v[38:41]
	v_mfma_f32_16x16x32_bf16 v[34:37], v[184:187], v[220:223], v[34:37]
	v_mfma_f32_16x16x32_bf16 v[22:25], v[176:179], v[228:231], v[22:25]
	v_mfma_f32_16x16x32_bf16 v[18:21], v[184:187], v[228:231], v[18:21]
	v_mfma_f32_16x16x32_bf16 v[6:9], v[176:179], v[236:239], v[6:9]
	v_mfma_f32_16x16x32_bf16 v[2:5], v[184:187], v[236:239], v[2:5]
	s_setprio 0
	s_barrier
	s_add_i32 s54, s54, 2
	s_add_u32 s26, s26, 0x100
	s_addc_u32 s27, s27, 0
	s_add_u32 s52, s52, 0x100
	s_addc_u32 s53, s53, 0
	s_cmp_gt_u32 s54, 5
	s_cbranch_scc0 .LBB0_107
	v_lshl_add_u32 v166, s49, 8, v146
	v_lshl_or_b32 v167, s48, 8, v148
	v_lshlrev_b32_e32 v167, 1, v167
	v_add_u32_e32 v199, 0, v166
	v_mad_u32_u24 v200, v199, s81, v167
	v_lshl_add_u32 v201, v199, 12, v167
	global_load_dwordx4 v[180:183], v200, s[10:11]
	global_load_dwordx4 v[184:187], v201, s[88:89]
	global_load_dwordx4 v[188:191], v200, s[10:11] offset:256
	global_load_dwordx4 v[212:215], v201, s[88:89] offset:256
	v_add_u32_e32 v199, 16, v166
	v_mad_u32_u24 v200, v199, s81, v167
	v_lshl_add_u32 v201, v199, 12, v167
	global_load_dwordx4 v[216:219], v200, s[10:11]
	global_load_dwordx4 v[220:223], v201, s[88:89]
	global_load_dwordx4 v[224:227], v200, s[10:11] offset:256
	global_load_dwordx4 v[228:231], v201, s[88:89] offset:256
	v_add_u32_e32 v199, 32, v166
	v_mad_u32_u24 v200, v199, s81, v167
	v_lshl_add_u32 v201, v199, 12, v167
	global_load_dwordx4 v[232:235], v200, s[10:11]
	global_load_dwordx4 v[236:239], v201, s[88:89]
	global_load_dwordx4 v[206:209], v200, s[10:11] offset:256
	global_load_dwordx4 v[246:249], v201, s[88:89] offset:256
	s_and_b64 vcc, exec, s[16:17]
	s_cbranch_vccz .LBB0_110
	s_barrier
; __device__ __forceinline__ u32x4 pack8(f32x4 a, f32x4 b) { u32x4 w; w.x = cvt_pk_bf16(a[0], a[1]); w.y = cvt_pk_bf16(a[2], a[3]); w.z = cvt_pk_bf16(b[0], b[1]); w.w = cvt_pk_bf16(b[2], b[3]); return w; }
; __device__ __forceinline__ void unpack8(u32x4 w, f32x4& a, f32x4& b) { a = (f32x4){bf_lo(w.x), bf_hi(w.x), bf_lo(w.y), bf_hi(w.y)}; b = (f32x4){bf_lo(w.z), bf_hi(w.z), bf_lo(w.w), bf_hi(w.w)}; }
;     __device__ __forceinline__ void operator()(const f32x4 (&acc)[2][2][4][2], const Unit& u, int wr, int wc, int fr, int fq) const {
;     ...
;                     } else if (MODE == EP_MERGE0 || MODE == EP_MERGE1) {
;                         f32x4 g0, g1; unpack8(*(const u32x4*)(aux + row * ldaux + col), g0, g1);
;                         v0 = g0 * v0; v1 = g1 * v1;
;                         if (MODE == EP_MERGE1) { f32x4 o0, o1; unpack8(*(const u32x4*)((const bf16_t*)O + row * ldc + col), o0, o1); v0 = v0 + o0; v1 = v1 + o1; }
;                         *(u32x4*)((bf16_t*)O + row * ldc + col) = pack8(v0, v1);
.LBB0_110:
	v_lshl_add_u32 v142, s49, 8, v146
	v_lshl_or_b32 v140, s48, 8, v148
	v_ashrrev_i32_e32 v143, 31, v142
	v_mov_b64_e32 v[144:145], s[10:11]
	v_ashrrev_i32_e32 v141, 31, v140
	v_lshlrev_b64 v[154:155], 12, v[142:143]
	v_mad_i64_i32 v[150:151], s[26:27], v142, s81, v[144:145]
	v_lshlrev_b64 v[140:141], 1, v[140:141]
	v_lshl_add_u64 v[154:155], s[88:89], 0, v[154:155]
	v_lshl_add_u64 v[168:169], v[150:151], 0, v[140:141]
	v_lshl_add_u64 v[170:171], v[154:155], 0, v[140:141]
	s_nop 0
	s_nop 0
	s_andn2_b64 vcc, exec, s[4:5]
	s_mov_b64 s[4:5], -1
	s_nop 0
	s_waitcnt vmcnt(10)
	v_lshlrev_b32_e32 v172, 16, v180
	v_and_b32_e32 v173, 0xffff0000, v180
	v_lshlrev_b32_e32 v150, 16, v181
	v_and_b32_e32 v151, 0xffff0000, v181
	v_lshlrev_b32_e32 v174, 16, v182
	v_and_b32_e32 v175, 0xffff0000, v182
	v_lshlrev_b32_e32 v152, 16, v183
	v_and_b32_e32 v153, 0xffff0000, v183
	v_lshlrev_b32_e32 v176, 16, v184
	v_and_b32_e32 v177, 0xffff0000, v184
	v_lshlrev_b32_e32 v154, 16, v185
	v_and_b32_e32 v155, 0xffff0000, v185
	v_lshlrev_b32_e32 v178, 16, v186
	v_and_b32_e32 v179, 0xffff0000, v186
	v_lshlrev_b32_e32 v156, 16, v187
	v_and_b32_e32 v157, 0xffff0000, v187
	v_add_u32_e32 v199, 48, v166
	v_mad_u32_u24 v200, v199, s81, v167
	v_lshl_add_u32 v201, v199, 12, v167
	global_load_dwordx4 v[180:183], v200, s[10:11]
	global_load_dwordx4 v[184:187], v201, s[88:89]
	v_pk_fma_f32 v[128:129], v[128:129], v[150:151], v[154:155]
	v_pk_fma_f32 v[126:127], v[126:127], v[172:173], v[176:177]
	v_pk_fma_f32 v[150:151], v[124:125], v[152:153], v[156:157]
	v_pk_fma_f32 v[124:125], v[122:123], v[174:175], v[178:179]
	v_cvt_pk_bf16_f32 v122, v126, v127
	v_cvt_pk_bf16_f32 v123, v128, v129
	v_or_b32_e32 v154, 16, v142
	v_cvt_pk_bf16_f32 v124, v124, v125
	v_cvt_pk_bf16_f32 v125, v150, v151
	s_nop 0
	s_nop 0
	v_ashrrev_i32_e32 v155, 31, v154
	global_store_dwordx4 v[170:171], v[122:125], off
	v_mad_i64_i32 v[156:157], s[26:27], v154, s81, v[144:145]
	v_lshl_add_u64 v[156:157], v[156:157], 0, v[140:141]
	s_nop 0
	s_waitcnt vmcnt(11)
	v_lshlrev_b32_e32 v122, 16, v188
	v_and_b32_e32 v123, 0xffff0000, v188
	v_lshlrev_b32_e32 v124, 16, v189
	v_and_b32_e32 v125, 0xffff0000, v189
	v_lshlrev_b32_e32 v126, 16, v190
	v_and_b32_e32 v127, 0xffff0000, v190
	v_lshlrev_b32_e32 v128, 16, v191
	v_and_b32_e32 v129, 0xffff0000, v191
	s_nop 0
	v_lshlrev_b32_e32 v168, 16, v212
	v_and_b32_e32 v169, 0xffff0000, v212
	v_lshlrev_b32_e32 v172, 16, v214
	v_and_b32_e32 v173, 0xffff0000, v214
	v_lshlrev_b32_e32 v152, 16, v215
	v_and_b32_e32 v153, 0xffff0000, v215
	v_lshlrev_b32_e32 v150, 16, v213
	v_and_b32_e32 v151, 0xffff0000, v213
	v_add_u32_e32 v199, 48, v166
	v_mad_u32_u24 v200, v199, s81, v167
	v_lshl_add_u32 v201, v199, 12, v167
	global_load_dwordx4 v[188:191], v200, s[10:11] offset:256
	global_load_dwordx4 v[212:215], v201, s[88:89] offset:256
	v_pk_fma_f32 v[118:119], v[118:119], v[122:123], v[168:169]
	v_pk_fma_f32 v[122:123], v[116:117], v[128:129], v[152:153]
	v_pk_fma_f32 v[116:117], v[114:115], v[126:127], v[172:173]
	v_pk_fma_f32 v[120:121], v[120:121], v[124:125], v[150:151]
	v_cvt_pk_bf16_f32 v114, v118, v119
	s_nop 0
	v_cvt_pk_bf16_f32 v115, v120, v121
	v_cvt_pk_bf16_f32 v116, v116, v117
	v_cvt_pk_bf16_f32 v117, v122, v123
	v_lshlrev_b64 v[122:123], 12, v[154:155]
	v_lshl_add_u64 v[122:123], s[88:89], 0, v[122:123]
	v_lshl_add_u64 v[126:127], v[122:123], 0, v[140:141]
	s_nop 0
	s_nop 0
	s_nop 0
	s_waitcnt vmcnt(11)
	v_lshlrev_b32_e32 v128, 16, v220
	global_store_dwordx4 v[170:171], v[114:117], off offset:256
	v_and_b32_e32 v129, 0xffff0000, v220
	v_lshlrev_b32_e32 v122, 16, v221
	v_lshlrev_b32_e32 v114, 16, v216
	v_and_b32_e32 v115, 0xffff0000, v216
	v_lshlrev_b32_e32 v116, 16, v217
	v_and_b32_e32 v117, 0xffff0000, v217
	v_lshlrev_b32_e32 v118, 16, v218
	v_and_b32_e32 v119, 0xffff0000, v218
	v_lshlrev_b32_e32 v120, 16, v219
	v_and_b32_e32 v121, 0xffff0000, v219
	v_and_b32_e32 v123, 0xffff0000, v221
	v_lshlrev_b32_e32 v150, 16, v222
	v_and_b32_e32 v151, 0xffff0000, v222
	v_lshlrev_b32_e32 v124, 16, v223
	v_and_b32_e32 v125, 0xffff0000, v223
	v_add_u32_e32 v199, 128, v166
	v_mad_u32_u24 v200, v199, s81, v167
	v_lshl_add_u32 v201, v199, 12, v167
	global_load_dwordx4 v[216:219], v200, s[10:11]
	global_load_dwordx4 v[220:223], v201, s[88:89]
	v_pk_fma_f32 v[112:113], v[112:113], v[116:117], v[122:123]
	v_pk_fma_f32 v[110:111], v[110:111], v[114:115], v[128:129]
	v_pk_fma_f32 v[114:115], v[108:109], v[120:121], v[124:125]
	v_pk_fma_f32 v[108:109], v[106:107], v[118:119], v[150:151]
	v_cvt_pk_bf16_f32 v106, v110, v111
	v_cvt_pk_bf16_f32 v107, v112, v113
	v_or_b32_e32 v118, 32, v142
	v_cvt_pk_bf16_f32 v108, v108, v109
	v_cvt_pk_bf16_f32 v109, v114, v115
	s_nop 0
	s_nop 0
	v_ashrrev_i32_e32 v119, 31, v118
	global_store_dwordx4 v[126:127], v[106:109], off
	v_mad_i64_i32 v[120:121], s[26:27], v118, s81, v[144:145]
	v_lshl_add_u64 v[120:121], v[120:121], 0, v[140:141]
	s_nop 0
	s_waitcnt vmcnt(13)
	v_lshlrev_b32_e32 v106, 16, v224
	v_and_b32_e32 v107, 0xffff0000, v224
	v_lshlrev_b32_e32 v108, 16, v225
	v_and_b32_e32 v109, 0xffff0000, v225
	v_lshlrev_b32_e32 v110, 16, v226
	v_and_b32_e32 v111, 0xffff0000, v226
	v_lshlrev_b32_e32 v112, 16, v227
	v_and_b32_e32 v113, 0xffff0000, v227
	s_nop 0
	v_lshlrev_b32_e32 v122, 16, v228
	v_and_b32_e32 v123, 0xffff0000, v228
	v_lshlrev_b32_e32 v124, 16, v230
	v_and_b32_e32 v125, 0xffff0000, v230
	v_lshlrev_b32_e32 v116, 16, v231
	v_and_b32_e32 v117, 0xffff0000, v231
	v_lshlrev_b32_e32 v114, 16, v229
	v_and_b32_e32 v115, 0xffff0000, v229
	v_add_u32_e32 v199, 128, v166
	v_mad_u32_u24 v200, v199, s81, v167
	v_lshl_add_u32 v201, v199, 12, v167
	global_load_dwordx4 v[224:227], v200, s[10:11] offset:256
	global_load_dwordx4 v[228:231], v201, s[88:89] offset:256
	v_pk_fma_f32 v[102:103], v[102:103], v[106:107], v[122:123]
	v_pk_fma_f32 v[106:107], v[100:101], v[112:113], v[116:117]
	v_pk_fma_f32 v[100:101], v[98:99], v[110:111], v[124:125]
	v_pk_fma_f32 v[104:105], v[104:105], v[108:109], v[114:115]
	v_cvt_pk_bf16_f32 v98, v102, v103
	s_nop 0
	v_cvt_pk_bf16_f32 v99, v104, v105
	v_cvt_pk_bf16_f32 v100, v100, v101
	v_cvt_pk_bf16_f32 v101, v106, v107
	v_lshlrev_b64 v[106:107], 12, v[118:119]
	v_lshl_add_u64 v[106:107], s[88:89], 0, v[106:107]
	v_lshl_add_u64 v[110:111], v[106:107], 0, v[140:141]
	s_nop 0
	s_nop 0
	s_nop 0
	s_waitcnt vmcnt(13)
; __device__ __forceinline__ u32x4 pack8(f32x4 a, f32x4 b) { u32x4 w; w.x = cvt_pk_bf16(a[0], a[1]); w.y = cvt_pk_bf16(a[2], a[3]); w.z = cvt_pk_bf16(b[0], b[1]); w.w = cvt_pk_bf16(b[2], b[3]); return w; }
; __device__ __forceinline__ void unpack8(u32x4 w, f32x4& a, f32x4& b) { a = (f32x4){bf_lo(w.x), bf_hi(w.x), bf_lo(w.y), bf_hi(w.y)}; b = (f32x4){bf_lo(w.z), bf_hi(w.z), bf_lo(w.w), bf_hi(w.w)}; }
;     __device__ __forceinline__ void operator()(const f32x4 (&acc)[2][2][4][2], const Unit& u, int wr, int wc, int fr, int fq) const {
;     ...
;                     } else if (MODE == EP_MERGE0 || MODE == EP_MERGE1) {
;                         f32x4 g0, g1; unpack8(*(const u32x4*)(aux + row * ldaux + col), g0, g1);
;                         v0 = g0 * v0; v1 = g1 * v1;
;                         if (MODE == EP_MERGE1) { f32x4 o0, o1; unpack8(*(const u32x4*)((const bf16_t*)O + row * ldc + col), o0, o1); v0 = v0 + o0; v1 = v1 + o1; }
;                         *(u32x4*)((bf16_t*)O + row * ldc + col) = pack8(v0, v1);
	v_lshlrev_b32_e32 v112, 16, v236
	global_store_dwordx4 v[126:127], v[98:101], off offset:256
	v_and_b32_e32 v113, 0xffff0000, v236
	v_lshlrev_b32_e32 v106, 16, v237
	v_lshlrev_b32_e32 v98, 16, v232
	v_and_b32_e32 v99, 0xffff0000, v232
	v_lshlrev_b32_e32 v100, 16, v233
	v_and_b32_e32 v101, 0xffff0000, v233
	v_lshlrev_b32_e32 v102, 16, v234
	v_and_b32_e32 v103, 0xffff0000, v234
	v_lshlrev_b32_e32 v104, 16, v235
	v_and_b32_e32 v105, 0xffff0000, v235
	v_and_b32_e32 v107, 0xffff0000, v237
	v_lshlrev_b32_e32 v114, 16, v238
	v_and_b32_e32 v115, 0xffff0000, v238
	v_lshlrev_b32_e32 v108, 16, v239
	v_and_b32_e32 v109, 0xffff0000, v239
	v_add_u32_e32 v199, 144, v166
	v_mad_u32_u24 v200, v199, s81, v167
	v_lshl_add_u32 v201, v199, 12, v167
	global_load_dwordx4 v[232:235], v200, s[10:11]
	global_load_dwordx4 v[236:239], v201, s[88:89]
	v_pk_fma_f32 v[96:97], v[96:97], v[100:101], v[106:107]
	v_pk_fma_f32 v[94:95], v[94:95], v[98:99], v[112:113]
	v_pk_fma_f32 v[98:99], v[92:93], v[104:105], v[108:109]
	v_pk_fma_f32 v[92:93], v[90:91], v[102:103], v[114:115]
	v_cvt_pk_bf16_f32 v90, v94, v95
	v_cvt_pk_bf16_f32 v91, v96, v97
	v_or_b32_e32 v102, 48, v142
	v_cvt_pk_bf16_f32 v92, v92, v93
	v_cvt_pk_bf16_f32 v93, v98, v99
	s_nop 0
	s_nop 0
	v_ashrrev_i32_e32 v103, 31, v102
	global_store_dwordx4 v[110:111], v[90:93], off
	v_mad_i64_i32 v[104:105], s[26:27], v102, s81, v[144:145]
	v_lshl_add_u64 v[104:105], v[104:105], 0, v[140:141]
	s_nop 0
	s_waitcnt vmcnt(15)
	v_lshlrev_b32_e32 v90, 16, v206
	v_and_b32_e32 v91, 0xffff0000, v206
	v_lshlrev_b32_e32 v92, 16, v207
	v_and_b32_e32 v93, 0xffff0000, v207
	v_lshlrev_b32_e32 v94, 16, v208
	v_and_b32_e32 v95, 0xffff0000, v208
	v_lshlrev_b32_e32 v96, 16, v209
	v_and_b32_e32 v97, 0xffff0000, v209
	s_nop 0
	v_lshlrev_b32_e32 v106, 16, v246
	v_and_b32_e32 v107, 0xffff0000, v246
	v_lshlrev_b32_e32 v108, 16, v248
	v_and_b32_e32 v109, 0xffff0000, v248
	v_lshlrev_b32_e32 v100, 16, v249
	v_and_b32_e32 v101, 0xffff0000, v249
	v_lshlrev_b32_e32 v98, 16, v247
	v_and_b32_e32 v99, 0xffff0000, v247
	v_add_u32_e32 v199, 144, v166
	v_mad_u32_u24 v200, v199, s81, v167
	v_lshl_add_u32 v201, v199, 12, v167
	global_load_dwordx4 v[206:209], v200, s[10:11] offset:256
	global_load_dwordx4 v[246:249], v201, s[88:89] offset:256
	v_pk_fma_f32 v[86:87], v[86:87], v[90:91], v[106:107]
	v_pk_fma_f32 v[90:91], v[84:85], v[96:97], v[100:101]
	v_pk_fma_f32 v[84:85], v[82:83], v[94:95], v[108:109]
	v_pk_fma_f32 v[88:89], v[88:89], v[92:93], v[98:99]
	v_cvt_pk_bf16_f32 v82, v86, v87
	s_nop 0
	v_cvt_pk_bf16_f32 v83, v88, v89
	v_cvt_pk_bf16_f32 v84, v84, v85
	v_cvt_pk_bf16_f32 v85, v90, v91
	v_lshlrev_b64 v[90:91], 12, v[102:103]
	v_lshl_add_u64 v[90:91], s[88:89], 0, v[90:91]
	v_lshl_add_u64 v[94:95], v[90:91], 0, v[140:141]
	s_nop 0
	s_nop 0
	s_nop 0
	s_waitcnt vmcnt(15)
	v_lshlrev_b32_e32 v96, 16, v184
	global_store_dwordx4 v[110:111], v[82:85], off offset:256
	v_and_b32_e32 v97, 0xffff0000, v184
	v_lshlrev_b32_e32 v90, 16, v185
	v_lshlrev_b32_e32 v82, 16, v180
	v_and_b32_e32 v83, 0xffff0000, v180
	v_lshlrev_b32_e32 v84, 16, v181
	v_and_b32_e32 v85, 0xffff0000, v181
	v_lshlrev_b32_e32 v86, 16, v182
	v_and_b32_e32 v87, 0xffff0000, v182
	v_lshlrev_b32_e32 v88, 16, v183
	v_and_b32_e32 v89, 0xffff0000, v183
	v_and_b32_e32 v91, 0xffff0000, v185
	v_lshlrev_b32_e32 v98, 16, v186
	v_and_b32_e32 v99, 0xffff0000, v186
	v_lshlrev_b32_e32 v92, 16, v187
	v_and_b32_e32 v93, 0xffff0000, v187
	v_add_u32_e32 v199, 160, v166
	v_mad_u32_u24 v200, v199, s81, v167
	v_lshl_add_u32 v201, v199, 12, v167
	global_load_dwordx4 v[180:183], v200, s[10:11]
	global_load_dwordx4 v[184:187], v201, s[88:89]
	v_pk_fma_f32 v[80:81], v[80:81], v[84:85], v[90:91]
	v_pk_fma_f32 v[78:79], v[78:79], v[82:83], v[96:97]
	v_pk_fma_f32 v[82:83], v[76:77], v[88:89], v[92:93]
	v_pk_fma_f32 v[76:77], v[74:75], v[86:87], v[98:99]
	v_cvt_pk_bf16_f32 v74, v78, v79
	v_cvt_pk_bf16_f32 v75, v80, v81
	v_add_u32_e32 v86, 0x80, v142
	v_cvt_pk_bf16_f32 v76, v76, v77
	v_cvt_pk_bf16_f32 v77, v82, v83
	s_nop 0
	s_nop 0
	v_ashrrev_i32_e32 v87, 31, v86
	global_store_dwordx4 v[94:95], v[74:77], off
	v_mad_i64_i32 v[88:89], s[26:27], v86, s81, v[144:145]
	v_lshl_add_u64 v[88:89], v[88:89], 0, v[140:141]
	s_nop 0
	s_waitcnt vmcnt(16)
	v_lshlrev_b32_e32 v74, 16, v188
	v_and_b32_e32 v75, 0xffff0000, v188
	s_nop 0
	v_lshlrev_b32_e32 v90, 16, v212
	v_and_b32_e32 v91, 0xffff0000, v212
	v_lshlrev_b32_e32 v76, 16, v189
	v_and_b32_e32 v77, 0xffff0000, v189
	v_lshlrev_b32_e32 v78, 16, v190
	v_and_b32_e32 v79, 0xffff0000, v190
	v_lshlrev_b32_e32 v80, 16, v191
	v_and_b32_e32 v81, 0xffff0000, v191
	v_lshlrev_b32_e32 v92, 16, v214
	v_and_b32_e32 v93, 0xffff0000, v214
	v_lshlrev_b32_e32 v84, 16, v215
	v_and_b32_e32 v85, 0xffff0000, v215
	v_pk_fma_f32 v[70:71], v[70:71], v[74:75], v[90:91]
	v_lshlrev_b32_e32 v82, 16, v213
	v_and_b32_e32 v83, 0xffff0000, v213
	v_add_u32_e32 v199, 160, v166
	v_mad_u32_u24 v200, v199, s81, v167
	v_lshl_add_u32 v201, v199, 12, v167
	global_load_dwordx4 v[188:191], v200, s[10:11] offset:256
	global_load_dwordx4 v[212:215], v201, s[88:89] offset:256
	v_pk_fma_f32 v[74:75], v[68:69], v[80:81], v[84:85]
	v_pk_fma_f32 v[68:69], v[66:67], v[78:79], v[92:93]
	v_cvt_pk_bf16_f32 v66, v70, v71
	v_lshlrev_b64 v[70:71], 12, v[86:87]
	v_pk_fma_f32 v[72:73], v[72:73], v[76:77], v[82:83]
	v_lshl_add_u64 v[70:71], s[88:89], 0, v[70:71]
	v_cvt_pk_bf16_f32 v67, v72, v73
	v_cvt_pk_bf16_f32 v68, v68, v69
	v_cvt_pk_bf16_f32 v69, v74, v75
	global_store_dwordx4 v[94:95], v[66:69], off offset:256
	v_lshl_add_u64 v[74:75], v[70:71], 0, v[140:141]
	s_nop 0
	s_nop 0
	s_nop 0
	s_waitcnt vmcnt(16)
; __device__ __forceinline__ u32x4 pack8(f32x4 a, f32x4 b) { u32x4 w; w.x = cvt_pk_bf16(a[0], a[1]); w.y = cvt_pk_bf16(a[2], a[3]); w.z = cvt_pk_bf16(b[0], b[1]); w.w = cvt_pk_bf16(b[2], b[3]); return w; }
; __device__ __forceinline__ void unpack8(u32x4 w, f32x4& a, f32x4& b) { a = (f32x4){bf_lo(w.x), bf_hi(w.x), bf_lo(w.y), bf_hi(w.y)}; b = (f32x4){bf_lo(w.z), bf_hi(w.z), bf_lo(w.w), bf_hi(w.w)}; }
;     __device__ __forceinline__ void operator()(const f32x4 (&acc)[2][2][4][2], const Unit& u, int wr, int wc, int fr, int fq) const {
;     ...
;                     } else if (MODE == EP_MERGE0 || MODE == EP_MERGE1) {
;                         f32x4 g0, g1; unpack8(*(const u32x4*)(aux + row * ldaux + col), g0, g1);
;                         v0 = g0 * v0; v1 = g1 * v1;
;                         if (MODE == EP_MERGE1) { f32x4 o0, o1; unpack8(*(const u32x4*)((const bf16_t*)O + row * ldc + col), o0, o1); v0 = v0 + o0; v1 = v1 + o1; }
;                         *(u32x4*)((bf16_t*)O + row * ldc + col) = pack8(v0, v1);
	v_lshlrev_b32_e32 v76, 16, v216
	v_and_b32_e32 v77, 0xffff0000, v216
	v_lshlrev_b32_e32 v66, 16, v217
	v_and_b32_e32 v67, 0xffff0000, v217
	v_lshlrev_b32_e32 v78, 16, v218
	v_and_b32_e32 v79, 0xffff0000, v218
	v_lshlrev_b32_e32 v68, 16, v219
	v_and_b32_e32 v69, 0xffff0000, v219
	s_nop 0
	v_lshlrev_b32_e32 v80, 16, v220
	v_and_b32_e32 v81, 0xffff0000, v220
	v_lshlrev_b32_e32 v70, 16, v221
	v_and_b32_e32 v71, 0xffff0000, v221
	v_lshlrev_b32_e32 v82, 16, v222
	v_and_b32_e32 v83, 0xffff0000, v222
	v_lshlrev_b32_e32 v72, 16, v223
	v_and_b32_e32 v73, 0xffff0000, v223
	v_add_u32_e32 v199, 176, v166
	v_mad_u32_u24 v200, v199, s81, v167
	v_lshl_add_u32 v201, v199, 12, v167
	global_load_dwordx4 v[216:219], v200, s[10:11]
	global_load_dwordx4 v[220:223], v201, s[88:89]
	v_pk_fma_f32 v[64:65], v[64:65], v[66:67], v[70:71]
	v_pk_fma_f32 v[62:63], v[62:63], v[76:77], v[80:81]
	v_pk_fma_f32 v[66:67], v[60:61], v[68:69], v[72:73]
	v_pk_fma_f32 v[60:61], v[58:59], v[78:79], v[82:83]
	v_cvt_pk_bf16_f32 v58, v62, v63
	v_cvt_pk_bf16_f32 v59, v64, v65
	v_add_u32_e32 v70, 0x90, v142
	v_cvt_pk_bf16_f32 v60, v60, v61
	v_cvt_pk_bf16_f32 v61, v66, v67
	s_nop 0
	s_nop 0
	v_ashrrev_i32_e32 v71, 31, v70
	global_store_dwordx4 v[74:75], v[58:61], off
	v_mad_i64_i32 v[72:73], s[26:27], v70, s81, v[144:145]
	v_lshl_add_u64 v[72:73], v[72:73], 0, v[140:141]
	s_nop 0
	s_waitcnt vmcnt(16)
	v_lshlrev_b32_e32 v58, 16, v224
	v_and_b32_e32 v59, 0xffff0000, v224
	v_lshlrev_b32_e32 v60, 16, v225
	v_and_b32_e32 v61, 0xffff0000, v225
	v_lshlrev_b32_e32 v62, 16, v226
	v_and_b32_e32 v63, 0xffff0000, v226
	v_lshlrev_b32_e32 v64, 16, v227
	v_and_b32_e32 v65, 0xffff0000, v227
	s_nop 0
	v_lshlrev_b32_e32 v76, 16, v228
	v_and_b32_e32 v77, 0xffff0000, v228
	v_lshlrev_b32_e32 v78, 16, v230
	v_and_b32_e32 v79, 0xffff0000, v230
	v_lshlrev_b32_e32 v68, 16, v231
	v_and_b32_e32 v69, 0xffff0000, v231
	v_lshlrev_b32_e32 v66, 16, v229
	v_and_b32_e32 v67, 0xffff0000, v229
	v_add_u32_e32 v199, 176, v166
	v_mad_u32_u24 v200, v199, s81, v167
	v_lshl_add_u32 v201, v199, 12, v167
	global_load_dwordx4 v[224:227], v200, s[10:11] offset:256
	global_load_dwordx4 v[228:231], v201, s[88:89] offset:256
	v_pk_fma_f32 v[54:55], v[54:55], v[58:59], v[76:77]
	v_pk_fma_f32 v[58:59], v[52:53], v[64:65], v[68:69]
	v_pk_fma_f32 v[52:53], v[50:51], v[62:63], v[78:79]
	v_pk_fma_f32 v[56:57], v[56:57], v[60:61], v[66:67]
	v_cvt_pk_bf16_f32 v50, v54, v55
	s_nop 0
	v_cvt_pk_bf16_f32 v51, v56, v57
	v_cvt_pk_bf16_f32 v52, v52, v53
	v_cvt_pk_bf16_f32 v53, v58, v59
	v_lshlrev_b64 v[58:59], 12, v[70:71]
	v_lshl_add_u64 v[58:59], s[88:89], 0, v[58:59]
	v_lshl_add_u64 v[62:63], v[58:59], 0, v[140:141]
	s_nop 0
	s_nop 0
	s_nop 0
	s_waitcnt vmcnt(15)
	v_lshlrev_b32_e32 v64, 16, v236
	global_store_dwordx4 v[74:75], v[50:53], off offset:256
	v_and_b32_e32 v65, 0xffff0000, v236
	v_lshlrev_b32_e32 v58, 16, v237
	v_lshlrev_b32_e32 v50, 16, v232
	v_and_b32_e32 v51, 0xffff0000, v232
	v_lshlrev_b32_e32 v52, 16, v233
	v_and_b32_e32 v53, 0xffff0000, v233
	v_lshlrev_b32_e32 v54, 16, v234
	v_and_b32_e32 v55, 0xffff0000, v234
	v_lshlrev_b32_e32 v56, 16, v235
	v_and_b32_e32 v57, 0xffff0000, v235
	v_and_b32_e32 v59, 0xffff0000, v237
	v_lshlrev_b32_e32 v66, 16, v238
	v_and_b32_e32 v67, 0xffff0000, v238
	v_lshlrev_b32_e32 v60, 16, v239
	v_and_b32_e32 v61, 0xffff0000, v239
	v_pk_fma_f32 v[48:49], v[48:49], v[52:53], v[58:59]
	v_pk_fma_f32 v[46:47], v[46:47], v[50:51], v[64:65]
	v_pk_fma_f32 v[50:51], v[44:45], v[56:57], v[60:61]
	v_pk_fma_f32 v[44:45], v[42:43], v[54:55], v[66:67]
	v_cvt_pk_bf16_f32 v42, v46, v47
	v_cvt_pk_bf16_f32 v43, v48, v49
	v_add_u32_e32 v54, 0xa0, v142
	v_cvt_pk_bf16_f32 v44, v44, v45
	v_cvt_pk_bf16_f32 v45, v50, v51
	s_nop 0
	s_nop 0
	v_ashrrev_i32_e32 v55, 31, v54
	global_store_dwordx4 v[62:63], v[42:45], off
	v_mad_i64_i32 v[56:57], s[26:27], v54, s81, v[144:145]
	v_lshl_add_u64 v[56:57], v[56:57], 0, v[140:141]
	s_nop 0
	s_waitcnt vmcnt(14)
	v_lshlrev_b32_e32 v42, 16, v206
	v_and_b32_e32 v43, 0xffff0000, v206
	v_lshlrev_b32_e32 v44, 16, v207
	v_and_b32_e32 v45, 0xffff0000, v207
	v_lshlrev_b32_e32 v46, 16, v208
	v_and_b32_e32 v47, 0xffff0000, v208
	v_lshlrev_b32_e32 v48, 16, v209
	v_and_b32_e32 v49, 0xffff0000, v209
	s_nop 0
	v_lshlrev_b32_e32 v58, 16, v246
	v_and_b32_e32 v59, 0xffff0000, v246
	v_lshlrev_b32_e32 v60, 16, v248
	v_and_b32_e32 v61, 0xffff0000, v248
	v_lshlrev_b32_e32 v52, 16, v249
	v_and_b32_e32 v53, 0xffff0000, v249
	v_lshlrev_b32_e32 v50, 16, v247
	v_and_b32_e32 v51, 0xffff0000, v247
	v_pk_fma_f32 v[38:39], v[38:39], v[42:43], v[58:59]
	v_pk_fma_f32 v[42:43], v[36:37], v[48:49], v[52:53]
	v_pk_fma_f32 v[36:37], v[34:35], v[46:47], v[60:61]
	v_pk_fma_f32 v[40:41], v[40:41], v[44:45], v[50:51]
	v_cvt_pk_bf16_f32 v34, v38, v39
	s_nop 0
	v_cvt_pk_bf16_f32 v35, v40, v41
	v_cvt_pk_bf16_f32 v36, v36, v37
	v_cvt_pk_bf16_f32 v37, v42, v43
	v_lshlrev_b64 v[42:43], 12, v[54:55]
	v_lshl_add_u64 v[42:43], s[88:89], 0, v[42:43]
	v_lshl_add_u64 v[46:47], v[42:43], 0, v[140:141]
	s_nop 0
	s_nop 0
	s_nop 0
	s_waitcnt vmcnt(11)
; __device__ __forceinline__ u32x4 pack8(f32x4 a, f32x4 b) { u32x4 w; w.x = cvt_pk_bf16(a[0], a[1]); w.y = cvt_pk_bf16(a[2], a[3]); w.z = cvt_pk_bf16(b[0], b[1]); w.w = cvt_pk_bf16(b[2], b[3]); return w; }
; __device__ __forceinline__ void unpack8(u32x4 w, f32x4& a, f32x4& b) { a = (f32x4){bf_lo(w.x), bf_hi(w.x), bf_lo(w.y), bf_hi(w.y)}; b = (f32x4){bf_lo(w.z), bf_hi(w.z), bf_lo(w.w), bf_hi(w.w)}; }
;     __device__ __forceinline__ void operator()(const f32x4 (&acc)[2][2][4][2], const Unit& u, int wr, int wc, int fr, int fq) const {
;     ...
;                     } else if (MODE == EP_MERGE0 || MODE == EP_MERGE1) {
;                         f32x4 g0, g1; unpack8(*(const u32x4*)(aux + row * ldaux + col), g0, g1);
;                         v0 = g0 * v0; v1 = g1 * v1;
;                         if (MODE == EP_MERGE1) { f32x4 o0, o1; unpack8(*(const u32x4*)((const bf16_t*)O + row * ldc + col), o0, o1); v0 = v0 + o0; v1 = v1 + o1; }
;                         *(u32x4*)((bf16_t*)O + row * ldc + col) = pack8(v0, v1);
	v_lshlrev_b32_e32 v48, 16, v184
	global_store_dwordx4 v[62:63], v[34:37], off offset:256
	v_and_b32_e32 v49, 0xffff0000, v184
	v_lshlrev_b32_e32 v42, 16, v185
	v_lshlrev_b32_e32 v34, 16, v180
	v_and_b32_e32 v35, 0xffff0000, v180
	v_lshlrev_b32_e32 v36, 16, v181
	v_and_b32_e32 v37, 0xffff0000, v181
	v_lshlrev_b32_e32 v38, 16, v182
	v_and_b32_e32 v39, 0xffff0000, v182
	v_lshlrev_b32_e32 v40, 16, v183
	v_and_b32_e32 v41, 0xffff0000, v183
	v_and_b32_e32 v43, 0xffff0000, v185
	v_lshlrev_b32_e32 v50, 16, v186
	v_and_b32_e32 v51, 0xffff0000, v186
	v_lshlrev_b32_e32 v44, 16, v187
	v_and_b32_e32 v45, 0xffff0000, v187
	v_pk_fma_f32 v[32:33], v[32:33], v[36:37], v[42:43]
	v_pk_fma_f32 v[30:31], v[30:31], v[34:35], v[48:49]
	v_pk_fma_f32 v[34:35], v[28:29], v[40:41], v[44:45]
	v_pk_fma_f32 v[28:29], v[26:27], v[38:39], v[50:51]
	v_cvt_pk_bf16_f32 v26, v30, v31
	v_cvt_pk_bf16_f32 v27, v32, v33
	v_add_u32_e32 v38, 0xb0, v142
	v_cvt_pk_bf16_f32 v28, v28, v29
	v_cvt_pk_bf16_f32 v29, v34, v35
	s_nop 0
	s_nop 0
	v_ashrrev_i32_e32 v39, 31, v38
	global_store_dwordx4 v[46:47], v[26:29], off
	v_mad_i64_i32 v[40:41], s[26:27], v38, s81, v[144:145]
	v_lshl_add_u64 v[40:41], v[40:41], 0, v[140:141]
	s_nop 0
	s_waitcnt vmcnt(10)
	v_lshlrev_b32_e32 v26, 16, v188
	v_and_b32_e32 v27, 0xffff0000, v188
	v_lshlrev_b32_e32 v28, 16, v189
	v_and_b32_e32 v29, 0xffff0000, v189
	v_lshlrev_b32_e32 v30, 16, v190
	v_and_b32_e32 v31, 0xffff0000, v190
	v_lshlrev_b32_e32 v32, 16, v191
	v_and_b32_e32 v33, 0xffff0000, v191
	s_nop 0
	v_lshlrev_b32_e32 v42, 16, v212
	v_and_b32_e32 v43, 0xffff0000, v212
	v_lshlrev_b32_e32 v44, 16, v214
	v_and_b32_e32 v45, 0xffff0000, v214
	v_lshlrev_b32_e32 v36, 16, v215
	v_and_b32_e32 v37, 0xffff0000, v215
	v_lshlrev_b32_e32 v34, 16, v213
	v_and_b32_e32 v35, 0xffff0000, v213
	v_pk_fma_f32 v[22:23], v[22:23], v[26:27], v[42:43]
	v_pk_fma_f32 v[26:27], v[20:21], v[32:33], v[36:37]
	v_pk_fma_f32 v[20:21], v[18:19], v[30:31], v[44:45]
	v_pk_fma_f32 v[24:25], v[24:25], v[28:29], v[34:35]
	v_cvt_pk_bf16_f32 v18, v22, v23
	s_nop 0
	v_cvt_pk_bf16_f32 v19, v24, v25
	v_cvt_pk_bf16_f32 v20, v20, v21
	v_cvt_pk_bf16_f32 v21, v26, v27
	v_lshlrev_b64 v[26:27], 12, v[38:39]
	v_lshl_add_u64 v[26:27], s[88:89], 0, v[26:27]
	v_lshl_add_u64 v[30:31], v[26:27], 0, v[140:141]
	s_nop 0
	s_nop 0
	s_nop 0
	s_waitcnt vmcnt(7)
	v_lshlrev_b32_e32 v32, 16, v220
	global_store_dwordx4 v[46:47], v[18:21], off offset:256
	v_and_b32_e32 v33, 0xffff0000, v220
	v_lshlrev_b32_e32 v26, 16, v221
	v_lshlrev_b32_e32 v18, 16, v216
	v_and_b32_e32 v19, 0xffff0000, v216
	v_lshlrev_b32_e32 v20, 16, v217
	v_and_b32_e32 v21, 0xffff0000, v217
	v_lshlrev_b32_e32 v22, 16, v218
	v_and_b32_e32 v23, 0xffff0000, v218
	v_lshlrev_b32_e32 v24, 16, v219
	v_and_b32_e32 v25, 0xffff0000, v219
	v_and_b32_e32 v27, 0xffff0000, v221
	v_lshlrev_b32_e32 v34, 16, v222
	v_and_b32_e32 v35, 0xffff0000, v222
	v_lshlrev_b32_e32 v28, 16, v223
	v_and_b32_e32 v29, 0xffff0000, v223
	v_pk_fma_f32 v[16:17], v[16:17], v[20:21], v[26:27]
	v_pk_fma_f32 v[14:15], v[14:15], v[18:19], v[32:33]
	v_pk_fma_f32 v[18:19], v[12:13], v[24:25], v[28:29]
	v_pk_fma_f32 v[12:13], v[10:11], v[22:23], v[34:35]
	v_cvt_pk_bf16_f32 v10, v14, v15
	v_cvt_pk_bf16_f32 v11, v16, v17
	s_nop 0
	v_cvt_pk_bf16_f32 v12, v12, v13
	v_cvt_pk_bf16_f32 v13, v18, v19
	s_nop 0
	s_nop 0
	s_nop 0
	s_waitcnt vmcnt(5)
	v_lshlrev_b32_e32 v22, 16, v228
	global_store_dwordx4 v[30:31], v[10:13], off
	v_and_b32_e32 v23, 0xffff0000, v228
	v_lshlrev_b32_e32 v24, 16, v230
	v_lshlrev_b32_e32 v10, 16, v224
	v_and_b32_e32 v11, 0xffff0000, v224
	v_lshlrev_b32_e32 v12, 16, v225
	v_and_b32_e32 v13, 0xffff0000, v225
	v_lshlrev_b32_e32 v14, 16, v226
	v_and_b32_e32 v15, 0xffff0000, v226
	v_lshlrev_b32_e32 v16, 16, v227
	v_and_b32_e32 v17, 0xffff0000, v227
	v_and_b32_e32 v25, 0xffff0000, v230
	v_lshlrev_b32_e32 v20, 16, v231
	v_and_b32_e32 v21, 0xffff0000, v231
	v_lshlrev_b32_e32 v18, 16, v229
	v_and_b32_e32 v19, 0xffff0000, v229
	v_pk_fma_f32 v[6:7], v[6:7], v[10:11], v[22:23]
	v_pk_fma_f32 v[10:11], v[4:5], v[16:17], v[20:21]
	v_pk_fma_f32 v[4:5], v[2:3], v[14:15], v[24:25]
	v_pk_fma_f32 v[8:9], v[8:9], v[12:13], v[18:19]
	v_cvt_pk_bf16_f32 v2, v6, v7
	s_nop 0
	v_cvt_pk_bf16_f32 v3, v8, v9
	v_cvt_pk_bf16_f32 v4, v4, v5
	v_cvt_pk_bf16_f32 v5, v10, v11
	global_store_dwordx4 v[30:31], v[2:5], off offset:256
	s_cbranch_vccnz .LBB0_99
	s_andn2_b64 vcc, exec, s[8:9]
	s_cbranch_vccnz .LBB0_98
	s_barrier
	s_branch .LBB0_98
